# setup phase now ends with the same XCD-hierarchical grid barrier as every other phase instead of the cooperative-groups grid sync
# baseline (speedup 1.0000x reference)
; __global__ void __launch_bounds__(NTHREADS) fwd_megakernel(Params P) {
;     ...
;         if (s == 0) gsync(grid);
;         else if (s < 44) xcd_barrier(xbar);
.LBB0_1162:
	v_readlane_b32 s4, v255, 26
	s_cmp_lg_u32 s4, -1
	s_mov_b64 s[2:3], -1
	s_cselect_b64 s[4:5], -1, 0
	s_andn2_b64 vcc, exec, s[4:5]
	s_cbranch_vccnz .LBB0_1160
